# XN (normalised bf16 activations) and bf16 weight-copy stores in P0 without the nt hint (consumed by the next GEMM phases); rsq fix-up removal in the FFN epilogue
# speedup vs baseline: 1.0095x; 1.0095x over previous
; __device__ __forceinline__ unsigned cvt_pk_bf16(float lo, float hi) { unsigned r; asm volatile("v_cvt_pk_bf16_f32 %0, %1, %2" : "=v"(r) : "v"(lo), "v"(hi)); return r; }
; __device__ __forceinline__ void p0_prologue(const Params& p, unsigned char* lds) {
;     ...
;         for (int m0 = 4 * gw; m0 < MT; m0 += 4 * NGW) {
;             int mm[4]; const float* xr[4];
; #pragma unroll
;             for (int q = 0; q < 4; ++q) { mm[q] = m0 + q;
;                 xr[q] = mm[q] < MP ? p.in[I_XP] + (size_t)mm[q] * DM : p.in[I_XS] + (size_t)(mm[q] - MP) * DM; }
;             f32x4 v[4][4];
; #pragma unroll
;             for (int q = 0; q < 4; ++q)
; #pragma unroll
;                 for (int j = 0; j < 4; ++j) v[q][j] = __builtin_nontemporal_load((const f32x4*)xr[q] + lane + 64 * j);
; #pragma unroll
;             for (int q = 0; q < 4; ++q) { float s = 0.f;
; #pragma unroll
;                 for (int j = 0; j < 4; ++j) s += (v[q][j][0] * v[q][j][0] + v[q][j][1] * v[q][j][1]) + (v[q][j][2] * v[q][j][2] + v[q][j][3] * v[q][j][3]);
;                 const float rstd = rsqrtf(wave_sum(s) * (1.0f / DM) + EPS);
;                 u32x2* o8 = (u32x2*)(XN + (size_t)mm[q] * DM) + lane;
; #pragma unroll
;                 for (int j = 0; j < 4; ++j) { u32x2 o; o.x = cvt_pk_bf16(v[q][j][0] * rstd * gv[j][0], v[q][j][1] * rstd * gv[j][1]); o.y = cvt_pk_bf16(v[q][j][2] * rstd * gv[j][2], v[q][j][3] * rstd * gv[j][3]); __builtin_nontemporal_store(o, o8 + 64 * j); } }
.LBB0_76:
	s_or_b64 exec, exec, s[4:5]
	v_add_u32_e32 v20, 0xffffbfff, v54
	v_lshl_add_u64 v[18:19], v[54:55], 0, -1
	v_cmp_gt_i32_e32 vcc, s1, v50
	v_lshl_add_u64 v[16:17], v[16:17], 0, v[178:179]
	v_lshl_add_u64 v[34:35], v[54:55], 0, 1
	v_cndmask_b32_e32 v19, 0, v19, vcc
	v_cndmask_b32_e32 v18, v20, v18, vcc
	v_cndmask_b32_e32 v21, v62, v63, vcc
	v_cndmask_b32_e32 v20, v64, v65, vcc
	v_lshlrev_b64 v[18:19], 12, v[18:19]
	v_lshl_add_u64 v[18:19], v[20:21], 0, v[18:19]
	v_lshl_add_u64 v[18:19], v[18:19], 0, v[178:179]
	global_load_dwordx4 v[66:69], v[18:19], off nt
	global_load_dwordx4 v[70:73], v[18:19], off offset:1024 nt
	global_load_dwordx4 v[74:77], v[18:19], off offset:3072 nt
	global_load_dwordx4 v[78:81], v[18:19], off offset:2048 nt
	v_add_u32_e32 v18, 0xffffc000, v54
	v_cmp_gt_i32_e32 vcc, s1, v54
	v_add_u32_e32 v38, 0xffffc001, v54
	v_add_co_u32_e64 v98, s[4:5], s16, v58
	v_cndmask_b32_e32 v33, 0, v55, vcc
	v_cndmask_b32_e32 v32, v18, v54, vcc
	v_cndmask_b32_e32 v37, v62, v63, vcc
	v_cndmask_b32_e32 v36, v64, v65, vcc
	v_lshlrev_b64 v[32:33], 12, v[32:33]
	v_lshl_add_u64 v[32:33], v[36:37], 0, v[32:33]
	v_lshl_add_u64 v[32:33], v[32:33], 0, v[178:179]
	global_load_dwordx4 v[28:31], v[16:17], off nt
	global_load_dwordx4 v[24:27], v[16:17], off offset:1024 nt
	global_load_dwordx4 v[20:23], v[16:17], off offset:2048 nt
	s_nop 0
	global_load_dwordx4 v[16:19], v[16:17], off offset:3072 nt
	s_nop 0
	global_load_dwordx4 v[82:85], v[32:33], off nt
	global_load_dwordx4 v[86:89], v[32:33], off offset:1024 nt
	global_load_dwordx4 v[90:93], v[32:33], off offset:2048 nt
	global_load_dwordx4 v[94:97], v[32:33], off offset:3072 nt
	v_cmp_gt_i32_e32 vcc, s1, v34
	v_addc_co_u32_e64 v99, s[4:5], -1, v59, s[4:5]
	s_nop 0
	v_cndmask_b32_e32 v35, 0, v35, vcc
	v_cndmask_b32_e32 v34, v38, v34, vcc
	v_cndmask_b32_e32 v39, v62, v63, vcc
	v_cndmask_b32_e32 v38, v64, v65, vcc
	v_lshlrev_b64 v[34:35], 12, v[34:35]
	v_lshl_add_u64 v[34:35], v[38:39], 0, v[34:35]
	v_lshl_add_u64 v[32:33], v[34:35], 0, v[178:179]
	v_add_u32_e32 v50, s8, v50
	v_lshl_add_u64 v[54:55], v[54:55], 0, s[8:9]
	v_lshl_add_u64 v[56:57], v[56:57], 0, s[10:11]
	s_waitcnt vmcnt(11)
	v_pk_mul_f32 v[34:35], v[68:69], v[68:69]
	v_pk_mul_f32 v[36:37], v[66:67], v[66:67]
	s_waitcnt vmcnt(10)
	v_pk_mul_f32 v[38:39], v[72:73], v[72:73]
	v_pk_mul_f32 v[40:41], v[70:71], v[70:71]
	v_pk_mov_b32 v[46:47], v[36:37], v[34:35] op_sel:[1,0]
	v_mov_b32_e32 v37, v35
	v_pk_mov_b32 v[34:35], v[40:41], v[38:39] op_sel:[1,0]
	v_mov_b32_e32 v41, v39
	s_waitcnt vmcnt(9)
	v_mul_f32_e32 v45, v74, v74
	s_waitcnt vmcnt(8)
	v_mul_f32_e32 v42, v79, v79
	v_mul_f32_e32 v44, v81, v81
	v_pk_add_f32 v[36:37], v[46:47], v[36:37]
	v_pk_add_f32 v[34:35], v[34:35], v[40:41]
	v_mul_f32_e32 v48, v75, v75
	v_mul_f32_e32 v100, v76, v76
	v_mul_f32_e32 v101, v77, v77
	v_pk_fma_f32 v[38:39], v[78:79], v[78:79], v[42:43] op_sel_hi:[1,1,0]
	v_pk_fma_f32 v[42:43], v[80:81], v[80:81], v[44:45] op_sel_hi:[1,1,0]
	v_pk_add_f32 v[36:37], v[36:37], v[36:37] op_sel:[0,1] op_sel_hi:[1,0]
	v_pk_add_f32 v[34:35], v[34:35], v[34:35] op_sel:[0,1] op_sel_hi:[1,0]
	v_mov_b32_e32 v39, v100
	v_mov_b32_e32 v43, v101
	v_mov_b32_e32 v37, v45
	v_mov_b32_e32 v35, v48
	v_pk_add_f32 v[38:39], v[38:39], v[42:43]
	v_pk_add_f32 v[34:35], v[36:37], v[34:35]
	s_nop 0
	v_pk_add_f32 v[34:35], v[34:35], v[38:39]
	s_nop 0
	v_add_f32_e32 v34, v34, v35
	s_nop 1
	v_add_f32_dpp v34, v34, v34 quad_perm:[1,0,3,2] row_mask:0xf bank_mask:0xf bound_ctrl:1
	s_nop 1
	v_add_f32_dpp v34, v34, v34 quad_perm:[2,3,0,1] row_mask:0xf bank_mask:0xf bound_ctrl:1
	s_nop 1
	v_add_f32_dpp v34, v34, v34 row_half_mirror row_mask:0xf bank_mask:0xf bound_ctrl:1
	s_nop 1
	v_add_f32_dpp v34, v34, v34 row_mirror row_mask:0xf bank_mask:0xf bound_ctrl:1
	s_nop 0
	v_readlane_b32 s18, v34, 16
	v_readlane_b32 s19, v34, 48
	v_readlane_b32 s4, v34, 0
	v_readlane_b32 s5, v34, 32
	v_mov_b32_e32 v34, s18
	v_mov_b32_e32 v35, s19
	v_pk_add_f32 v[34:35], s[4:5], v[34:35]
	s_nop 0
	v_add_f32_e32 v34, v34, v35
	v_fmamk_f32 v34, v34, 0x3a800000, v51
	v_mul_f32_e32 v35, 0x4b800000, v34
	v_cmp_gt_f32_e32 vcc, s3, v34
	s_nop 1
	v_cndmask_b32_e32 v34, v34, v35, vcc
	v_rsq_f32_e32 v48, v34
	global_load_dwordx4 v[44:47], v[32:33], off nt
	global_load_dwordx4 v[40:43], v[32:33], off offset:1024 nt
	global_load_dwordx4 v[36:39], v[32:33], off offset:2048 nt
	s_nop 0
	global_load_dwordx4 v[32:35], v[32:33], off offset:3072 nt
	v_mul_f32_e32 v100, 0x45800000, v48
	v_cndmask_b32_e32 v48, v48, v100, vcc
	v_mul_f32_e32 v66, v66, v48
	v_mul_f32_e32 v67, v67, v48
	v_mul_f32_e32 v68, v68, v48
	v_mul_f32_e32 v69, v69, v48
	v_mul_f32_e32 v66, v12, v66
	v_mul_f32_e32 v67, v13, v67
	v_mul_f32_e32 v72, v72, v48
	v_mul_f32_e32 v68, v14, v68
	v_mul_f32_e32 v69, v15, v69
	v_cvt_pk_bf16_f32 v66, v66, v67
	v_cvt_pk_bf16_f32 v67, v68, v69
	v_mul_f32_e32 v70, v70, v48
	v_mul_f32_e32 v71, v71, v48
	global_store_dwordx2 v[98:99], v[66:67], off offset:-1536
	v_mul_f32_e32 v67, v10, v72
	v_mul_f32_e32 v68, v73, v48
	v_mul_f32_e32 v70, v8, v70
	v_mul_f32_e32 v71, v9, v71
	v_cvt_pk_bf16_f32 v66, v70, v71
	v_mul_f32_e32 v68, v11, v68
	v_cvt_pk_bf16_f32 v67, v67, v68
	global_store_dwordx2 v[98:99], v[66:67], off offset:-1024
	v_mul_f32_e32 v66, v78, v48
	v_mul_f32_e32 v67, v79, v48
	v_mul_f32_e32 v66, v4, v66
	v_mul_f32_e32 v67, v5, v67
	v_cvt_pk_bf16_f32 v66, v66, v67
	v_mul_f32_e32 v67, v80, v48
	v_mul_f32_e32 v68, v81, v48
	v_mul_f32_e32 v67, v6, v67
	v_mul_f32_e32 v68, v7, v68
	v_cvt_pk_bf16_f32 v67, v67, v68
	s_waitcnt vmcnt(9)
; __device__ __forceinline__ unsigned cvt_pk_bf16(float lo, float hi) { unsigned r; asm volatile("v_cvt_pk_bf16_f32 %0, %1, %2" : "=v"(r) : "v"(lo), "v"(hi)); return r; }
; __device__ __forceinline__ void p0_prologue(const Params& p, unsigned char* lds) {
;     ...
;             for (int q = 0; q < 4; ++q)
; #pragma unroll
;                 for (int j = 0; j < 4; ++j) v[q][j] = __builtin_nontemporal_load((const f32x4*)xr[q] + lane + 64 * j);
; #pragma unroll
;             for (int q = 0; q < 4; ++q) { float s = 0.f;
; #pragma unroll
;                 for (int j = 0; j < 4; ++j) s += (v[q][j][0] * v[q][j][0] + v[q][j][1] * v[q][j][1]) + (v[q][j][2] * v[q][j][2] + v[q][j][3] * v[q][j][3]);
;                 const float rstd = rsqrtf(wave_sum(s) * (1.0f / DM) + EPS);
;                 u32x2* o8 = (u32x2*)(XN + (size_t)mm[q] * DM) + lane;
; #pragma unroll
;                 for (int j = 0; j < 4; ++j) { u32x2 o; o.x = cvt_pk_bf16(v[q][j][0] * rstd * gv[j][0], v[q][j][1] * rstd * gv[j][1]); o.y = cvt_pk_bf16(v[q][j][2] * rstd * gv[j][2], v[q][j][3] * rstd * gv[j][3]); __builtin_nontemporal_store(o, o8 + 64 * j); } }
	v_pk_mul_f32 v[68:69], v[84:85], v[84:85]
	v_pk_mul_f32 v[70:71], v[82:83], v[82:83]
	global_store_dwordx2 v[98:99], v[66:67], off offset:-512
	v_pk_mov_b32 v[72:73], v[70:71], v[68:69] op_sel:[1,0]
	v_mov_b32_e32 v71, v69
	v_pk_add_f32 v[68:69], v[72:73], v[70:71]
	s_waitcnt vmcnt(9)
	v_pk_mul_f32 v[70:71], v[88:89], v[88:89]
	v_pk_mul_f32 v[72:73], v[86:87], v[86:87]
	v_mul_f32_e32 v66, v74, v48
	v_mul_f32_e32 v67, v75, v48
	v_pk_mov_b32 v[74:75], v[72:73], v[70:71] op_sel:[1,0]
	v_mov_b32_e32 v73, v71
	v_mul_f32_e32 v66, v0, v66
	v_mul_f32_e32 v67, v1, v67
	v_pk_add_f32 v[70:71], v[74:75], v[72:73]
	v_cvt_pk_bf16_f32 v66, v66, v67
	v_mul_f32_e32 v67, v76, v48
	v_mul_f32_e32 v76, v77, v48
	s_waitcnt vmcnt(7)
	v_mul_f32_e32 v48, v94, v94
	v_mul_f32_e32 v72, v95, v95
	v_pk_add_f32 v[68:69], v[68:69], v[68:69] op_sel:[0,1] op_sel_hi:[1,0]
	v_pk_add_f32 v[70:71], v[70:71], v[70:71] op_sel:[0,1] op_sel_hi:[1,0]
	v_mov_b32_e32 v69, v48
	v_mov_b32_e32 v71, v72
	v_mul_f32_e32 v48, v91, v91
	v_mul_f32_e32 v73, v96, v96
	v_pk_add_f32 v[68:69], v[68:69], v[70:71]
	v_pk_fma_f32 v[70:71], v[90:91], v[90:91], v[48:49] op_sel_hi:[1,1,0]
	v_mul_f32_e32 v48, v93, v93
	v_mul_f32_e32 v74, v97, v97
	v_mov_b32_e32 v71, v73
	v_pk_fma_f32 v[72:73], v[92:93], v[92:93], v[48:49] op_sel_hi:[1,1,0]
	v_mul_f32_e32 v67, v2, v67
	v_mov_b32_e32 v73, v74
	v_pk_add_f32 v[70:71], v[70:71], v[72:73]
	s_nop 0
	v_pk_add_f32 v[68:69], v[68:69], v[70:71]
	s_waitcnt vmcnt(6)
	v_pk_mul_f32 v[70:71], v[44:45], v[44:45]
	v_add_f32_e32 v48, v68, v69
	s_nop 1
	v_add_f32_dpp v48, v48, v48 quad_perm:[1,0,3,2] row_mask:0xf bank_mask:0xf bound_ctrl:1
	s_nop 1
	v_add_f32_dpp v48, v48, v48 quad_perm:[2,3,0,1] row_mask:0xf bank_mask:0xf bound_ctrl:1
	s_nop 1
	v_add_f32_dpp v48, v48, v48 row_half_mirror row_mask:0xf bank_mask:0xf bound_ctrl:1
	s_nop 1
	v_add_f32_dpp v48, v48, v48 row_mirror row_mask:0xf bank_mask:0xf bound_ctrl:1
	s_nop 0
	v_readlane_b32 s18, v48, 16
	v_readlane_b32 s19, v48, 48
	v_readlane_b32 s4, v48, 0
	v_readlane_b32 s5, v48, 32
	v_mov_b32_e32 v68, s18
	v_mov_b32_e32 v69, s19
	v_pk_add_f32 v[68:69], s[4:5], v[68:69]
	s_nop 0
	v_add_f32_e32 v48, v68, v69
	v_fmamk_f32 v48, v48, 0x3a800000, v51
	v_mul_f32_e32 v68, 0x4b800000, v48
	v_cmp_gt_f32_e32 vcc, s3, v48
	s_nop 1
	v_cndmask_b32_e32 v48, v48, v68, vcc
	v_rsq_f32_e32 v48, v48
	v_mul_f32_e32 v68, v3, v76
	v_cvt_pk_bf16_f32 v67, v67, v68
	global_store_dwordx2 v[58:59], v[66:67], off offset:-4096
	v_mul_f32_e32 v66, 0x45800000, v48
	v_cndmask_b32_e32 v48, v48, v66, vcc
	v_mul_f32_e32 v66, v82, v48
	v_mul_f32_e32 v67, v83, v48
	v_mul_f32_e32 v66, v12, v66
	v_mul_f32_e32 v67, v13, v67
	v_cvt_pk_bf16_f32 v66, v66, v67
	v_mul_f32_e32 v67, v84, v48
	v_mul_f32_e32 v67, v14, v67
	v_mul_f32_e32 v68, v85, v48
	v_mul_f32_e32 v68, v15, v68
	v_cvt_pk_bf16_f32 v67, v67, v68
	global_store_dwordx2 v[58:59], v[66:67], off offset:-3584
	v_mul_f32_e32 v66, v86, v48
	v_mul_f32_e32 v67, v87, v48
	v_mul_f32_e32 v66, v8, v66
	v_mul_f32_e32 v67, v9, v67
	v_cvt_pk_bf16_f32 v66, v66, v67
	v_mul_f32_e32 v67, v88, v48
	v_mul_f32_e32 v67, v10, v67
	v_mul_f32_e32 v68, v89, v48
	v_mul_f32_e32 v68, v11, v68
	v_cvt_pk_bf16_f32 v67, v67, v68
	global_store_dwordx2 v[58:59], v[66:67], off offset:-3072
	v_mul_f32_e32 v66, v90, v48
	v_mul_f32_e32 v67, v91, v48
	v_mul_f32_e32 v66, v4, v66
	v_mul_f32_e32 v67, v5, v67
	v_cvt_pk_bf16_f32 v66, v66, v67
	v_mul_f32_e32 v67, v92, v48
	v_mul_f32_e32 v68, v93, v48
	v_mul_f32_e32 v67, v6, v67
	v_mul_f32_e32 v68, v7, v68
	v_cvt_pk_bf16_f32 v67, v67, v68
	v_pk_mul_f32 v[68:69], v[46:47], v[46:47]
	global_store_dwordx2 v[58:59], v[66:67], off offset:-2560
	v_pk_mov_b32 v[72:73], v[70:71], v[68:69] op_sel:[1,0]
	v_mov_b32_e32 v71, v69
	v_pk_add_f32 v[68:69], v[72:73], v[70:71]
	s_waitcnt vmcnt(9)
	v_pk_mul_f32 v[70:71], v[42:43], v[42:43]
	v_pk_mul_f32 v[72:73], v[40:41], v[40:41]
	v_mul_f32_e32 v66, v94, v48
	v_mul_f32_e32 v67, v95, v48
	v_pk_mov_b32 v[74:75], v[72:73], v[70:71] op_sel:[1,0]
	v_mov_b32_e32 v73, v71
	v_mul_f32_e32 v66, v0, v66
	v_mul_f32_e32 v67, v1, v67
	v_pk_add_f32 v[70:71], v[74:75], v[72:73]
	v_cvt_pk_bf16_f32 v66, v66, v67
	v_mul_f32_e32 v67, v96, v48
	v_mul_f32_e32 v76, v97, v48
	s_waitcnt vmcnt(7)
; __device__ __forceinline__ unsigned cvt_pk_bf16(float lo, float hi) { unsigned r; asm volatile("v_cvt_pk_bf16_f32 %0, %1, %2" : "=v"(r) : "v"(lo), "v"(hi)); return r; }
; __device__ __forceinline__ void p0_prologue(const Params& p, unsigned char* lds) {
;     ...
;             for (int q = 0; q < 4; ++q) { float s = 0.f;
; #pragma unroll
;                 for (int j = 0; j < 4; ++j) s += (v[q][j][0] * v[q][j][0] + v[q][j][1] * v[q][j][1]) + (v[q][j][2] * v[q][j][2] + v[q][j][3] * v[q][j][3]);
;                 const float rstd = rsqrtf(wave_sum(s) * (1.0f / DM) + EPS);
;                 u32x2* o8 = (u32x2*)(XN + (size_t)mm[q] * DM) + lane;
; #pragma unroll
;                 for (int j = 0; j < 4; ++j) { u32x2 o; o.x = cvt_pk_bf16(v[q][j][0] * rstd * gv[j][0], v[q][j][1] * rstd * gv[j][1]); o.y = cvt_pk_bf16(v[q][j][2] * rstd * gv[j][2], v[q][j][3] * rstd * gv[j][3]); __builtin_nontemporal_store(o, o8 + 64 * j); } }
	v_mul_f32_e32 v48, v32, v32
	v_mul_f32_e32 v72, v33, v33
	v_pk_add_f32 v[68:69], v[68:69], v[68:69] op_sel:[0,1] op_sel_hi:[1,0]
	v_pk_add_f32 v[70:71], v[70:71], v[70:71] op_sel:[0,1] op_sel_hi:[1,0]
	v_mov_b32_e32 v69, v48
	v_mov_b32_e32 v71, v72
	v_mul_f32_e32 v48, v37, v37
	v_mul_f32_e32 v73, v34, v34
	v_pk_add_f32 v[68:69], v[68:69], v[70:71]
	v_pk_fma_f32 v[70:71], v[36:37], v[36:37], v[48:49] op_sel_hi:[1,1,0]
	v_mul_f32_e32 v48, v39, v39
	v_mul_f32_e32 v74, v35, v35
	v_mov_b32_e32 v71, v73
	v_pk_fma_f32 v[72:73], v[38:39], v[38:39], v[48:49] op_sel_hi:[1,1,0]
	v_mul_f32_e32 v67, v2, v67
	v_mov_b32_e32 v73, v74
	v_pk_add_f32 v[70:71], v[70:71], v[72:73]
	s_nop 0
	v_pk_add_f32 v[68:69], v[68:69], v[70:71]
	s_nop 0
	v_add_f32_e32 v48, v68, v69
	s_nop 1
	v_add_f32_dpp v48, v48, v48 quad_perm:[1,0,3,2] row_mask:0xf bank_mask:0xf bound_ctrl:1
	s_nop 1
	v_add_f32_dpp v48, v48, v48 quad_perm:[2,3,0,1] row_mask:0xf bank_mask:0xf bound_ctrl:1
	s_nop 1
	v_add_f32_dpp v48, v48, v48 row_half_mirror row_mask:0xf bank_mask:0xf bound_ctrl:1
	s_nop 1
	v_add_f32_dpp v48, v48, v48 row_mirror row_mask:0xf bank_mask:0xf bound_ctrl:1
	s_nop 0
	v_readlane_b32 s18, v48, 16
	v_readlane_b32 s19, v48, 48
	v_readlane_b32 s4, v48, 0
	v_readlane_b32 s5, v48, 32
	v_mov_b32_e32 v68, s18
	v_mov_b32_e32 v69, s19
	v_pk_add_f32 v[68:69], s[4:5], v[68:69]
	s_nop 0
	v_add_f32_e32 v48, v68, v69
	v_fmamk_f32 v48, v48, 0x3a800000, v51
	v_mul_f32_e32 v68, 0x4b800000, v48
	v_cmp_gt_f32_e32 vcc, s3, v48
	s_nop 1
	v_cndmask_b32_e32 v48, v48, v68, vcc
	v_rsq_f32_e32 v48, v48
	v_mul_f32_e32 v68, v3, v76
	v_cvt_pk_bf16_f32 v67, v67, v68
	global_store_dwordx2 v[58:59], v[66:67], off offset:-2048
	v_mul_f32_e32 v66, 0x45800000, v48
	v_cndmask_b32_e32 v48, v48, v66, vcc
	v_mul_f32_e32 v44, v44, v48
	v_mul_f32_e32 v45, v45, v48
	v_mul_f32_e32 v44, v12, v44
	v_mul_f32_e32 v45, v13, v45
	v_cvt_pk_bf16_f32 v44, v44, v45
	v_mul_f32_e32 v45, v46, v48
	v_mul_f32_e32 v40, v40, v48
	v_mul_f32_e32 v41, v41, v48
	v_mul_f32_e32 v45, v14, v45
	v_mul_f32_e32 v46, v47, v48
	v_mul_f32_e32 v40, v8, v40
	v_mul_f32_e32 v41, v9, v41
	v_mul_f32_e32 v46, v15, v46
	v_cvt_pk_bf16_f32 v45, v45, v46
	global_store_dwordx2 v[58:59], v[44:45], off offset:-1536
	v_cvt_pk_bf16_f32 v40, v40, v41
	v_mul_f32_e32 v41, v42, v48
	v_mul_f32_e32 v36, v36, v48
	v_mul_f32_e32 v37, v37, v48
	v_mul_f32_e32 v41, v10, v41
	v_mul_f32_e32 v42, v43, v48
	v_mul_f32_e32 v36, v4, v36
	v_mul_f32_e32 v37, v5, v37
	v_mul_f32_e32 v42, v11, v42
	v_cvt_pk_bf16_f32 v41, v41, v42
	global_store_dwordx2 v[58:59], v[40:41], off offset:-1024
	v_cvt_pk_bf16_f32 v36, v36, v37
	v_mul_f32_e32 v37, v38, v48
	v_mul_f32_e32 v37, v6, v37
	v_mul_f32_e32 v38, v39, v48
	v_mul_f32_e32 v32, v32, v48
	v_mul_f32_e32 v33, v33, v48
	v_mul_f32_e32 v38, v7, v38
	v_cvt_pk_bf16_f32 v37, v37, v38
	v_mul_f32_e32 v32, v0, v32
	v_mul_f32_e32 v33, v1, v33
	global_store_dwordx2 v[58:59], v[36:37], off offset:-512
	v_cvt_pk_bf16_f32 v32, v32, v33
	v_mul_f32_e32 v33, v34, v48
	v_mul_f32_e32 v42, v35, v48
	v_pk_mul_f32 v[34:35], v[30:31], v[30:31]
	v_pk_mul_f32 v[36:37], v[28:29], v[28:29]
	v_mul_f32_e32 v33, v2, v33
	v_pk_mov_b32 v[38:39], v[36:37], v[34:35] op_sel:[1,0]
	v_mov_b32_e32 v37, v35
	v_pk_add_f32 v[34:35], v[38:39], v[36:37]
	v_pk_mul_f32 v[36:37], v[26:27], v[26:27]
	v_pk_mul_f32 v[38:39], v[24:25], v[24:25]
	v_pk_add_f32 v[34:35], v[34:35], v[34:35] op_sel:[0,1] op_sel_hi:[1,0]
	v_pk_mov_b32 v[40:41], v[38:39], v[36:37] op_sel:[1,0]
	v_mov_b32_e32 v39, v37
	v_pk_add_f32 v[36:37], v[40:41], v[38:39]
	v_mul_f32_e32 v38, v16, v16
	v_mul_f32_e32 v39, v17, v17
	v_pk_add_f32 v[36:37], v[36:37], v[36:37] op_sel:[0,1] op_sel_hi:[1,0]
	v_mov_b32_e32 v35, v38
	v_mov_b32_e32 v37, v39
	v_pk_add_f32 v[34:35], v[34:35], v[36:37]
	v_mul_f32_e32 v36, v21, v21
	v_mul_f32_e32 v38, v23, v23
	v_mul_f32_e32 v40, v18, v18
	v_mul_f32_e32 v41, v19, v19
	v_pk_fma_f32 v[36:37], v[20:21], v[20:21], v[36:37] op_sel_hi:[1,1,0]
	v_pk_fma_f32 v[38:39], v[22:23], v[22:23], v[38:39] op_sel_hi:[1,1,0]
	v_mov_b32_e32 v37, v40
	v_mov_b32_e32 v39, v41
	v_pk_add_f32 v[36:37], v[36:37], v[38:39]
	s_nop 0
	v_pk_add_f32 v[34:35], v[34:35], v[36:37]
	s_nop 0
	v_add_f32_e32 v34, v34, v35
	s_nop 1
	v_add_f32_dpp v34, v34, v34 quad_perm:[1,0,3,2] row_mask:0xf bank_mask:0xf bound_ctrl:1
	s_nop 1
	v_add_f32_dpp v34, v34, v34 quad_perm:[2,3,0,1] row_mask:0xf bank_mask:0xf bound_ctrl:1
	s_nop 1
	v_add_f32_dpp v34, v34, v34 row_half_mirror row_mask:0xf bank_mask:0xf bound_ctrl:1
	s_nop 1
	v_add_f32_dpp v34, v34, v34 row_mirror row_mask:0xf bank_mask:0xf bound_ctrl:1
	s_nop 0
	v_readlane_b32 s18, v34, 16
	v_readlane_b32 s19, v34, 48
	v_readlane_b32 s4, v34, 0
	v_readlane_b32 s5, v34, 32
	v_mov_b32_e32 v34, s18
	v_mov_b32_e32 v35, s19
	v_pk_add_f32 v[34:35], s[4:5], v[34:35]
	s_nop 0
	v_add_f32_e32 v34, v34, v35
	v_fmamk_f32 v34, v34, 0x3a800000, v51
	v_mul_f32_e32 v35, 0x4b800000, v34
	v_cmp_gt_f32_e32 vcc, s3, v34
	s_nop 1
	v_cndmask_b32_e32 v34, v34, v35, vcc
	v_rsq_f32_e32 v34, v34
	v_mul_f32_e32 v35, v3, v42
	v_cvt_pk_bf16_f32 v33, v33, v35
	global_store_dwordx2 v[58:59], v[32:33], off
	v_mul_f32_e32 v32, 0x45800000, v34
	v_cndmask_b32_e32 v34, v34, v32, vcc
	v_mul_f32_e32 v28, v28, v34
	v_mul_f32_e32 v29, v29, v34
	v_mul_f32_e32 v28, v12, v28
	v_mul_f32_e32 v29, v13, v29
	v_lshlrev_b64 v[32:33], 11, v[60:61]
	v_cvt_pk_bf16_f32 v28, v28, v29
	v_mul_f32_e32 v29, v30, v34
	v_mul_f32_e32 v24, v24, v34
	v_mul_f32_e32 v25, v25, v34
	v_lshl_add_u64 v[32:33], v[52:53], 0, v[32:33]
	v_mul_f32_e32 v29, v14, v29
	v_mul_f32_e32 v30, v31, v34
	v_mul_f32_e32 v24, v8, v24
	v_mul_f32_e32 v25, v9, v25
	v_mul_f32_e32 v30, v15, v30
	v_cvt_pk_bf16_f32 v29, v29, v30
	global_store_dwordx2 v[32:33], v[28:29], off
	v_cvt_pk_bf16_f32 v24, v24, v25
	v_mul_f32_e32 v25, v26, v34
	v_mul_f32_e32 v20, v20, v34
	v_mul_f32_e32 v21, v21, v34
	v_mul_f32_e32 v25, v10, v25
	v_mul_f32_e32 v26, v27, v34
	v_mul_f32_e32 v20, v4, v20
	v_mul_f32_e32 v21, v5, v21
	v_mul_f32_e32 v26, v11, v26
	v_cvt_pk_bf16_f32 v25, v25, v26
	global_store_dwordx2 v[32:33], v[24:25], off offset:512
	v_cvt_pk_bf16_f32 v20, v20, v21
	v_mul_f32_e32 v21, v22, v34
	v_mul_f32_e32 v16, v16, v34
	v_mul_f32_e32 v17, v17, v34
	v_mul_f32_e32 v21, v6, v21
	v_mul_f32_e32 v22, v23, v34
	v_mul_f32_e32 v16, v0, v16
	v_mul_f32_e32 v17, v1, v17
	v_mul_f32_e32 v22, v7, v22
	v_cvt_pk_bf16_f32 v21, v21, v22
	global_store_dwordx2 v[32:33], v[20:21], off offset:1024
	v_cvt_pk_bf16_f32 v16, v16, v17
	v_mul_f32_e32 v17, v18, v34
	v_cmp_lt_i32_e32 vcc, s17, v50
	v_mul_f32_e32 v17, v2, v17
	v_mul_f32_e32 v18, v19, v34
	s_or_b64 s[14:15], vcc, s[14:15]
	v_lshl_add_u64 v[58:59], v[58:59], 0, s[12:13]
	v_mul_f32_e32 v18, v3, v18
	v_cvt_pk_bf16_f32 v17, v17, v18
	global_store_dwordx2 v[32:33], v[16:17], off offset:1536
	s_andn2_b64 exec, exec, s[14:15]
	s_cbranch_execz .LBB0_79

; __device__ __forceinline__ unsigned cvt_pk_bf16(float lo, float hi) { unsigned r; asm volatile("v_cvt_pk_bf16_f32 %0, %1, %2" : "=v"(r) : "v"(lo), "v"(hi)); return r; }
; __device__ __forceinline__ void p0_prologue(const Params& p, unsigned char* lds) {
;     ...
;             for (int q = 0; q < 4; ++q) { float s = 0.f;
; #pragma unroll
;                 for (int j = 0; j < 4; ++j) s += (v[q][j][0] * v[q][j][0] + v[q][j][1] * v[q][j][1]) + (v[q][j][2] * v[q][j][2] + v[q][j][3] * v[q][j][3]);
;                 const float rstd = rsqrtf(wave_sum(s) * (1.0f / DM) + EPS);
;                 u32x2* o8 = (u32x2*)(XN + (size_t)mm[q] * DM) + lane;
; #pragma unroll
;                 for (int j = 0; j < 4; ++j) { u32x2 o; o.x = cvt_pk_bf16(v[q][j][0] * rstd * gv[j][0], v[q][j][1] * rstd * gv[j][1]); o.y = cvt_pk_bf16(v[q][j][2] * rstd * gv[j][2], v[q][j][3] * rstd * gv[j][3]); __builtin_nontemporal_store(o, o8 + 64 * j); } }
.LBB0_79:
	s_or_b64 exec, exec, s[6:7]
	s_cmp_lg_u32 s66, 0x100
	s_cbranch_scc1 .Lxs_end
	s_cmp_gt_u32 s20, 0x1ff
	s_cbranch_scc1 .Lxs_end
	s_waitcnt vmcnt(16)
	v_mul_f32_e32 v136, v104, v104
	v_fmac_f32_e32 v136, v105, v105
	v_fmac_f32_e32 v136, v106, v106
	v_fmac_f32_e32 v136, v107, v107
	v_fmac_f32_e32 v136, v108, v108
	v_fmac_f32_e32 v136, v109, v109
	v_fmac_f32_e32 v136, v110, v110
	v_fmac_f32_e32 v136, v111, v111
	v_fmac_f32_e32 v136, v112, v112
	v_fmac_f32_e32 v136, v113, v113
	v_fmac_f32_e32 v136, v114, v114
	v_fmac_f32_e32 v136, v115, v115
	v_fmac_f32_e32 v136, v116, v116
	v_fmac_f32_e32 v136, v117, v117
	v_fmac_f32_e32 v136, v118, v118
	v_fmac_f32_e32 v136, v119, v119
	s_nop 1
	v_add_f32_dpp v136, v136, v136 quad_perm:[1,0,3,2] row_mask:0xf bank_mask:0xf bound_ctrl:1
	s_nop 1
	v_add_f32_dpp v136, v136, v136 quad_perm:[2,3,0,1] row_mask:0xf bank_mask:0xf bound_ctrl:1
	s_nop 1
	v_add_f32_dpp v136, v136, v136 row_half_mirror row_mask:0xf bank_mask:0xf bound_ctrl:1
	s_nop 1
	v_add_f32_dpp v136, v136, v136 row_mirror row_mask:0xf bank_mask:0xf bound_ctrl:1
	s_nop 1
	v_readlane_b32 s28, v136, 0
	v_readlane_b32 s29, v136, 16
	v_readlane_b32 s30, v136, 32
	v_readlane_b32 s31, v136, 48
	s_add_i32 s21, s20, 0x4000
	s_lshl_b32 s21, s21, 11
	s_add_u32 s26, s64, s21
	s_addc_u32 s27, s65, 0
	s_add_u32 s26, s26, 0x96f5e00
	s_addc_u32 s27, s27, 0
	v_mov_b32_e32 v138, s29
	v_mov_b32_e32 v139, s31
	v_add_f32_e32 v138, s28, v138
	v_add_f32_e32 v139, s30, v139
	v_add_f32_e32 v138, v138, v139
	v_mov_b32_e32 v139, 0x358637bd
	v_fmac_f32_e32 v139, 0x3a800000, v138
	v_lshlrev_b32_e32 v137, 3, v206
	v_rsq_f32_e32 v139, v139
	s_nop 0
	v_mul_f32_e32 v104, v104, v139
	v_mul_f32_e32 v105, v105, v139
	v_mul_f32_e32 v106, v106, v139
	v_mul_f32_e32 v107, v107, v139
	v_mul_f32_e32 v108, v108, v139
	v_mul_f32_e32 v109, v109, v139
	v_mul_f32_e32 v110, v110, v139
	v_mul_f32_e32 v111, v111, v139
	v_mul_f32_e32 v112, v112, v139
	v_mul_f32_e32 v113, v113, v139
	v_mul_f32_e32 v114, v114, v139
	v_mul_f32_e32 v115, v115, v139
	v_mul_f32_e32 v116, v116, v139
	v_mul_f32_e32 v117, v117, v139
	v_mul_f32_e32 v118, v118, v139
	v_mul_f32_e32 v119, v119, v139
	v_mul_f32_e32 v104, v104, v120
	v_mul_f32_e32 v105, v105, v121
	v_mul_f32_e32 v106, v106, v122
	v_mul_f32_e32 v107, v107, v123
	v_mul_f32_e32 v108, v108, v124
	v_mul_f32_e32 v109, v109, v125
	v_mul_f32_e32 v110, v110, v126
	v_mul_f32_e32 v111, v111, v127
	v_mul_f32_e32 v112, v112, v128
	v_mul_f32_e32 v113, v113, v129
	v_mul_f32_e32 v114, v114, v130
	v_mul_f32_e32 v115, v115, v131
	v_mul_f32_e32 v116, v116, v132
	v_mul_f32_e32 v117, v117, v133
	v_mul_f32_e32 v118, v118, v134
	v_mul_f32_e32 v119, v119, v135
	v_cvt_pk_bf16_f32 v104, v104, v105
	v_cvt_pk_bf16_f32 v105, v106, v107
	global_store_dwordx2 v137, v[104:105], s[26:27]
	v_cvt_pk_bf16_f32 v108, v108, v109
	v_cvt_pk_bf16_f32 v109, v110, v111
	global_store_dwordx2 v137, v[108:109], s[26:27] offset:512
	v_cvt_pk_bf16_f32 v112, v112, v113
	v_cvt_pk_bf16_f32 v113, v114, v115
	global_store_dwordx2 v137, v[112:113], s[26:27] offset:1024
	v_cvt_pk_bf16_f32 v116, v116, v117
	v_cvt_pk_bf16_f32 v117, v118, v119
	global_store_dwordx2 v137, v[116:117], s[26:27] offset:1536

; __device__ __forceinline__ void p0_prologue(const Params& p, unsigned char* lds) {
;     ...
;     { float* scs = p.out + O_SCS; const float* sc = p.in[I_SC]; constexpr int RW = (CW - 1 - DS) * MIXB / 4; constexpr size_t NCP = (size_t)DB * RW;
;       for (size_t i0 = gt; i0 < NCP; i0 += 4 * NT) { f32x4 v[4]; size_t d[4];
; #pragma unroll
;           for (int q = 0; q < 4; ++q) { const size_t i = i0 + q * NT < NCP ? i0 + q * NT : i0, n = i / RW, w = i % RW; d[q] = n * (CW - 1) * MIXB + w * 4; v[q] = __builtin_nontemporal_load((const f32x4*)(sc + d[q] + DS * MIXB)); }
; #pragma unroll
;           for (int q = 0; q < 4; ++q) __builtin_nontemporal_store(v[q], (f32x4*)(scs + d[q])); } }
.LBB0_89:
	v_mul_hi_u32 v2, v0, s0
	v_lshl_add_u64 v[4:5], v[0:1], 0, s[4:5]
	v_lshrrev_b32_e32 v2, 10, v2
	v_cmp_gt_u64_e32 vcc, s[6:7], v[4:5]
	v_lshl_add_u64 v[6:7], v[4:5], 0, s[4:5]
	v_lshl_add_u64 v[20:21], v[6:7], 0, s[4:5]
	v_cndmask_b32_e32 v12, v1, v5, vcc
	v_mul_u32_u24_e32 v5, 0xd00, v2
	v_cndmask_b32_e32 v16, v0, v4, vcc
	v_cmp_gt_u64_e32 vcc, s[6:7], v[6:7]
	v_sub_u32_e32 v4, v0, v5
	v_mov_b32_e32 v9, v3
	v_cndmask_b32_e32 v17, v1, v7, vcc
	v_cndmask_b32_e32 v18, v0, v6, vcc
	v_cmp_gt_u64_e32 vcc, s[6:7], v[20:21]
	v_mov_b32_e32 v11, v3
	v_mov_b32_e32 v13, v3
	v_cndmask_b32_e32 v19, v1, v21, vcc
	v_lshlrev_b32_e32 v1, 2, v4
	v_mad_u32_u24 v2, v2, s3, v1
	v_lshlrev_b64 v[22:23], 2, v[2:3]
	v_mul_hi_u32 v2, v16, s17
	v_mad_u64_u32 v[4:5], s[20:21], v12, s17, v[2:3]
	v_cndmask_b32_e32 v28, v0, v20, vcc
	v_lshl_add_u64 v[0:1], s[22:23], 0, v[22:23]
	v_mov_b32_e32 v2, v5
	v_mov_b32_e32 v5, v3
	v_add_co_u32_e32 v0, vcc, 0x2000, v0
	v_mad_u64_u32 v[14:15], s[20:21], v16, s18, v[4:5]
	s_nop 0
	v_addc_co_u32_e32 v1, vcc, 0, v1, vcc
	v_mov_b32_e32 v8, v15
	global_load_dwordx4 v[4:7], v[0:1], off nt
	v_lshl_add_u64 v[0:1], v[2:3], 0, v[8:9]
	v_mul_hi_u32 v2, v18, s17
	v_mad_u64_u32 v[0:1], s[20:21], v12, s18, v[0:1]
	v_mad_u64_u32 v[8:9], s[20:21], v17, s17, v[2:3]
	v_alignbit_b32 v14, v1, v0, 10
	v_mov_b32_e32 v2, v9
	v_mov_b32_e32 v9, v3
	v_lshrrev_b32_e32 v15, 10, v1
	v_mad_u64_u32 v[0:1], s[20:21], v14, s1, 0
	v_mad_u64_u32 v[8:9], s[20:21], v18, s18, v[8:9]
	v_mad_u32_u24 v1, v15, s1, v1
	v_mov_b32_e32 v10, v9
	v_sub_co_u32_e32 v0, vcc, v16, v0
	v_lshl_add_u64 v[8:9], v[2:3], 0, v[10:11]
	s_nop 0
	v_subb_co_u32_e32 v1, vcc, v12, v1, vcc
	v_mul_hi_u32 v2, v28, s17
	v_lshlrev_b64 v[0:1], 2, v[0:1]
	v_mad_u64_u32 v[8:9], s[20:21], v17, s18, v[8:9]
	v_mad_u64_u32 v[10:11], s[20:21], v19, s17, v[2:3]
	v_mad_u64_u32 v[0:1], s[20:21], v14, s3, v[0:1]
	v_alignbit_b32 v14, v9, v8, 10
	v_mov_b32_e32 v2, v11
	v_mov_b32_e32 v11, v3
	v_lshrrev_b32_e32 v16, 10, v9
	v_mad_u32_u24 v1, v15, s3, v1
	v_mad_u64_u32 v[8:9], s[20:21], v14, s1, 0
	v_mad_u64_u32 v[10:11], s[20:21], v28, s18, v[10:11]
	v_lshlrev_b64 v[24:25], 2, v[0:1]
	v_mad_u32_u24 v1, v16, s1, v9
	v_sub_co_u32_e32 v0, vcc, v18, v8
	v_mov_b32_e32 v12, v11
	s_nop 0
	v_subb_co_u32_e32 v1, vcc, v17, v1, vcc
	v_lshl_add_u64 v[10:11], v[2:3], 0, v[12:13]
	v_lshl_add_u64 v[8:9], s[22:23], 0, v[24:25]
	v_lshlrev_b64 v[0:1], 2, v[0:1]
	v_mad_u64_u32 v[12:13], s[20:21], v19, s18, v[10:11]
	v_add_co_u32_e32 v8, vcc, s16, v8
	v_mad_u64_u32 v[0:1], s[20:21], v14, s3, v[0:1]
	v_alignbit_b32 v2, v13, v12, 10
	v_addc_co_u32_e32 v9, vcc, 0, v9, vcc
	v_lshrrev_b32_e32 v17, 10, v13
	v_mad_u32_u24 v1, v16, s3, v1
	v_mad_u64_u32 v[12:13], s[20:21], v2, s1, 0
	v_lshlrev_b64 v[26:27], 2, v[0:1]
	v_mad_u32_u24 v1, v17, s1, v13
	v_sub_co_u32_e32 v0, vcc, v28, v12
	v_lshl_add_u64 v[12:13], s[22:23], 0, v[26:27]
	s_nop 0
	v_subb_co_u32_e32 v1, vcc, v19, v1, vcc
	v_lshlrev_b64 v[0:1], 2, v[0:1]
	v_mad_u64_u32 v[0:1], s[20:21], v2, s3, v[0:1]
	v_mad_u32_u24 v1, v17, s3, v1
	v_add_co_u32_e32 v12, vcc, s16, v12
	v_lshlrev_b64 v[28:29], 2, v[0:1]
	s_nop 0
	v_addc_co_u32_e32 v13, vcc, 0, v13, vcc
	v_lshl_add_u64 v[0:1], s[22:23], 0, v[28:29]
	global_load_dwordx4 v[8:11], v[8:9], off nt
	v_add_co_u32_e32 v0, vcc, s16, v0
	global_load_dwordx4 v[12:15], v[12:13], off nt
	s_nop 0
	v_addc_co_u32_e32 v1, vcc, 0, v1, vcc
	global_load_dwordx4 v[16:19], v[0:1], off nt
	v_lshl_add_u64 v[0:1], v[20:21], 0, s[4:5]
	v_cmp_lt_u64_e32 vcc, s[14:15], v[0:1]
	s_or_b64 s[12:13], vcc, s[12:13]
	v_lshl_add_u64 v[20:21], s[8:9], 0, v[22:23]
	v_lshl_add_u64 v[22:23], s[8:9], 0, v[24:25]
	v_lshl_add_u64 v[24:25], s[8:9], 0, v[26:27]
	v_lshl_add_u64 v[26:27], s[8:9], 0, v[28:29]
	s_waitcnt vmcnt(3)
	global_store_dwordx4 v[20:21], v[4:7], off
	s_waitcnt vmcnt(3)
	global_store_dwordx4 v[22:23], v[8:11], off
	s_waitcnt vmcnt(3)
	global_store_dwordx4 v[24:25], v[12:15], off
	s_waitcnt vmcnt(3)
	global_store_dwordx4 v[26:27], v[16:19], off
	s_andn2_b64 exec, exec, s[12:13]
	s_cbranch_execnz .LBB0_89
